# In1 epilogue k_r/f_logit tiles: loop-invariant forget-bias vector loaded once at the epilogue head instead of per row behind the stores
# speedup vs baseline: 1.0016x; 1.0016x over previous
; #define LAS __attribute__((address_space(3)))
; template <int NP> __device__ __forceinline__ void row_scales(float (&rs)[2][4], const float* base, long row0, int fq, float inv_n) {
;     float t[2][4];
; #pragma unroll
;     for (int ai = 0; ai < 2; ++ai)
; #pragma unroll
;         for (int m = 0; m < 4; ++m) { const long row = row0 + ai * 128 + m * 16;
;             if (NP == 16) { const f32x4 v = *(const f32x4*)(base + row * 16 + 4 * fq); t[ai][m] = (v.x + v.y) + (v.z + v.w); }
;             else if (NP == 8) { const f32x2 v = *(const f32x2*)(base + row * 8 + 2 * fq); t[ai][m] = v.x + v.y; }
;             else t[ai][m] = base[row * 4 + fq]; }
; #pragma unroll
;     for (int ai = 0; ai < 2; ++ai)
; #pragma unroll
;         for (int m = 0; m < 4; ++m) rs[ai][m] = rsqrtf(red_fq(t[ai][m]) * inv_n + EPS);
;     __device__ __forceinline__ void operator()(AccT& acc, const Unit& u, int wr, int wc, int fr, int fq, LAS unsigned char*) const {
;         const long row0 = (long)u.pm * 256 + wr * 64 + fr;
;         float rsa[2][4]; row_scales<16>(rsa, ssqx, row0, fq, 1.f / 1024.f);
; #pragma unroll
;         for (int ai = 0; ai < 2; ++ai)
; #pragma unroll
;             for (int m = 0; m < 4; ++m) {
;                 const long row = row0 + ai * 128 + m * 16;
;                 const float rs = rsa[ai][m];
;                 f32x4 v[2][2];
; #pragma unroll
;                 for (int bj = 0; bj < 2; ++bj)
; #pragma unroll
;                     for (int n = 0; n < 2; ++n) v[bj][n] = acc[ai][bj][m][n] * rs;
;                 const int cl = wc * 32 + 8 * fq;
;                 if (u.pn == 0 || u.pn == 2 || u.pn == 5 || u.pn == 6) {
.LBB0_640:
	s_ashr_i32 s1, s0, 31
	s_lshl_b64 s[0:1], s[0:1], 8
	v_lshl_add_u64 v[156:157], s[0:1], 0, v[136:137]
	v_lshlrev_b64 v[176:177], 6, v[156:157]
	v_lshl_add_u64 v[170:171], v[144:145], 0, v[176:177]
	global_load_dwordx4 v[158:161], v[170:171], off
	s_movk_i32 s0, 0x2000
	v_add_co_u32_e32 v178, vcc, s0, v170
	s_mov_b32 s0, 0x3a800000
	s_nop 0
	v_addc_co_u32_e32 v179, vcc, 0, v171, vcc
	global_load_dwordx4 v[208:211], v[170:171], off offset:1024
	global_load_dwordx4 v[212:215], v[170:171], off offset:2048
	global_load_dwordx4 v[216:219], v[170:171], off offset:3072
	global_load_dwordx4 v[220:223], v[178:179], off
	global_load_dwordx4 v[224:227], v[178:179], off offset:1024
	global_load_dwordx4 v[228:231], v[178:179], off offset:2048
	global_load_dwordx4 v[232:235], v[178:179], off offset:3072
	global_load_dwordx4 v[200:203], v1, s[90:91]
	s_cmp_lg_u32 s18, 0
	s_cselect_b64 s[16:17], -1, 0
	s_cmp_eq_u32 s18, 3
	s_cselect_b64 s[42:43], -1, 0
	s_mov_b64 s[8:9], -1
	s_mov_b64 s[22:23], 0
	s_cmp_lt_i32 s18, 2
	s_mov_b64 s[12:13], 0
	s_mov_b64 s[78:79], 0
	s_waitcnt vmcnt(0)
	v_mov_b32_e32 v162, v159
	v_mov_b32_e32 v163, v160
	v_mov_b32_e32 v159, v161
	v_pk_add_f32 v[158:159], v[162:163], v[158:159]
	s_nop 0
	v_pk_add_f32 v[162:163], v[158:159], v[158:159] op_sel:[0,1] op_sel_hi:[1,0]
	v_mov_b64_e32 v[158:159], v[208:209]
	v_mov_b64_e32 v[160:161], v[210:211]
	v_mov_b32_e32 v0, v162
	s_nop 1
	v_permlane16_swap_b32_e32 v162, v0
	v_mov_b32_e32 v164, v159
	v_mov_b32_e32 v165, v160
	v_mov_b32_e32 v159, v161
	v_pk_add_f32 v[158:159], v[164:165], v[158:159]
	s_nop 0
	v_pk_add_f32 v[166:167], v[158:159], v[158:159] op_sel:[0,1] op_sel_hi:[1,0]
	v_mov_b64_e32 v[158:159], v[212:213]
	v_mov_b64_e32 v[160:161], v[214:215]
	v_mov_b32_e32 v164, v159
	v_mov_b32_e32 v165, v160
	v_mov_b32_e32 v159, v161
	v_pk_add_f32 v[158:159], v[164:165], v[158:159]
	s_nop 0
	v_pk_add_f32 v[168:169], v[158:159], v[158:159] op_sel:[0,1] op_sel_hi:[1,0]
	v_mov_b64_e32 v[158:159], v[216:217]
	v_mov_b64_e32 v[160:161], v[218:219]
	v_mov_b32_e32 v164, v159
	v_mov_b32_e32 v165, v160
	v_mov_b32_e32 v159, v161
	v_pk_add_f32 v[158:159], v[164:165], v[158:159]
	s_nop 0
	v_pk_add_f32 v[164:165], v[158:159], v[158:159] op_sel:[0,1] op_sel_hi:[1,0]
	v_mov_b64_e32 v[158:159], v[220:221]
	v_mov_b64_e32 v[160:161], v[222:223]
	v_mov_b32_e32 v170, v159
	v_mov_b32_e32 v171, v160
	v_mov_b32_e32 v159, v161
	v_pk_add_f32 v[158:159], v[170:171], v[158:159]
	s_nop 0
	v_pk_add_f32 v[170:171], v[158:159], v[158:159] op_sel:[0,1] op_sel_hi:[1,0]
	v_mov_b64_e32 v[158:159], v[224:225]
	v_mov_b64_e32 v[160:161], v[226:227]
	v_mov_b32_e32 v172, v159
	v_mov_b32_e32 v173, v160
	v_mov_b32_e32 v159, v161
	v_pk_add_f32 v[158:159], v[172:173], v[158:159]
	v_mov_b64_e32 v[172:173], v[228:229]
	v_mov_b64_e32 v[174:175], v[230:231]
	v_pk_add_f32 v[158:159], v[158:159], v[158:159] op_sel:[0,1] op_sel_hi:[1,0]
	v_mov_b32_e32 v160, v173
	v_mov_b32_e32 v161, v174
	v_mov_b32_e32 v173, v175
	v_pk_add_f32 v[160:161], v[160:161], v[172:173]
	v_mov_b64_e32 v[172:173], v[232:233]
	v_mov_b64_e32 v[174:175], v[234:235]
	v_pk_add_f32 v[160:161], v[160:161], v[160:161] op_sel:[0,1] op_sel_hi:[1,0]
	v_mov_b32_e32 v178, v173
	v_mov_b32_e32 v179, v174
	v_mov_b32_e32 v173, v175
	v_pk_add_f32 v[172:173], v[178:179], v[172:173]
	s_nop 0
	v_pk_add_f32 v[178:179], v[172:173], v[172:173] op_sel:[0,1] op_sel_hi:[1,0]
	v_add_f32_e32 v173, v162, v0
	v_mov_b32_e32 v0, v166
	s_nop 1
	v_permlane16_swap_b32_e32 v166, v0
	v_add_f32_e32 v172, v166, v0
	v_mov_b32_e32 v0, v168
	s_nop 1
	v_permlane16_swap_b32_e32 v168, v0
	v_add_f32_e32 v167, v168, v0
	v_mov_b32_e32 v0, v164
	s_nop 1
	v_permlane16_swap_b32_e32 v164, v0
	v_add_f32_e32 v166, v164, v0
	v_mov_b32_e32 v0, v170
	s_nop 1
	v_permlane16_swap_b32_e32 v170, v0
	v_add_f32_e32 v163, v170, v0
	v_mov_b32_e32 v0, v158
	s_nop 1
	v_permlane16_swap_b32_e32 v158, v0
	v_add_f32_e32 v162, v158, v0
	v_mov_b32_e32 v0, v160
	s_nop 1
	v_permlane16_swap_b32_e32 v160, v0
	v_mov_b32_e32 v175, v173
	v_mov_b32_e32 v174, v172
	v_add_f32_e32 v159, v160, v0
	v_mov_b32_e32 v0, v178
	v_permlane32_swap_b32_e32 v173, v175
	v_permlane32_swap_b32_e32 v172, v174
	v_permlane16_swap_b32_e32 v178, v0
	v_add_f32_e32 v158, v178, v0
	v_pk_add_f32 v[170:171], v[172:173], v[174:175]
	v_mov_b32_e32 v169, v167
	v_mov_b32_e32 v168, v166
	v_mov_b32_e32 v165, v163
	v_mov_b32_e32 v164, v162
	v_mov_b32_e32 v161, v159
	v_mov_b32_e32 v160, v158
	v_pk_fma_f32 v[170:171], v[170:171], s[0:1], v[194:195] op_sel_hi:[1,0,0]
	v_permlane32_swap_b32_e32 v167, v169
	v_permlane32_swap_b32_e32 v166, v168
	v_permlane32_swap_b32_e32 v163, v165
	v_permlane32_swap_b32_e32 v162, v164
	v_permlane32_swap_b32_e32 v159, v161
	v_permlane32_swap_b32_e32 v158, v160
	v_cmp_gt_f32_e64 s[44:45], s33, v170
	v_cmp_gt_f32_e64 s[0:1], s33, v171
	s_cbranch_scc1 .LBB0_653
	s_cmp_gt_i32 s18, 4
	s_cbranch_scc0 .LBB0_647
	s_cmp_gt_i32 s18, 5
	s_cbranch_scc0 .LBB0_648
	s_mov_b64 s[78:79], -1
	s_mov_b64 s[8:9], 0
	s_cmp_eq_u32 s18, 6
	s_cbranch_scc0 .LBB0_645
	v_readlane_b32 s12, v255, 48
	v_lshlrev_b64 v[172:173], 9, v[156:157]
	v_readlane_b32 s13, v255, 49
	s_mov_b64 s[78:79], 0
	s_nop 0
	v_lshl_add_u64 v[172:173], s[12:13], 0, v[172:173]
	s_mov_b64 s[12:13], -1

;     __device__ __forceinline__ void operator()(AccT& acc, const Unit& u, int wr, int wc, int fr, int fq, LAS unsigned char*) const {
;     ...
;                     } else if (wc == 1 && fq == 0) {
;                         const f32x4 fb = *(const f32x4*)fbias; f32x4 z = v[1][0] + fb, o;
; #pragma unroll
;                         for (int i = 0; i < 4; ++i) o[i] = fminf(z[i], 0.f) - 0.6931471805599453f * __builtin_amdgcn_logf(1.f + __builtin_amdgcn_exp2f(-fabsf(z[i]) * LOG2E));
;                         *(f32x4*)(logf + row * 4) = o;
;                     }
.LBB0_657:
	s_or_b64 exec, exec, s[0:1]
	s_and_b64 vcc, exec, s[70:71]
	s_cbranch_vccz .LBB0_661
	s_and_saveexec_b64 s[0:1], s[72:73]
	s_cbranch_execz .LBB0_660
	v_mov_b64_e32 v[178:179], v[200:201]
	v_mov_b64_e32 v[180:181], v[202:203]
	s_mov_b32 s2, 0xbfb8aa3b
	v_add_f32_e32 v0, v122, v178
	v_add_f32_e32 v171, v123, v179
	v_add_f32_e32 v182, v120, v180
	v_add_f32_e32 v183, v121, v181
	v_min_f32_e32 v114, 0, v0
	v_mul_f32_e64 v0, |v0|, s2
	v_min_f32_e32 v115, 0, v171
	v_mul_f32_e64 v171, |v171|, s2
	v_mul_f32_e64 v178, |v182|, s2
	v_mul_f32_e64 v179, |v183|, s2
	v_exp_f32_e32 v0, v0
	v_exp_f32_e32 v171, v171
	v_exp_f32_e32 v178, v178
	v_exp_f32_e32 v179, v179
	v_add_f32_e32 v0, 1.0, v0
	v_add_f32_e32 v171, 1.0, v171
	v_add_f32_e32 v180, 1.0, v178
	v_add_f32_e32 v179, 1.0, v179
	v_log_f32_e32 v178, v0
	v_log_f32_e32 v180, v180
	v_log_f32_e32 v181, v179
	v_log_f32_e32 v179, v171
	v_min_f32_e32 v182, 0, v182
	v_min_f32_e32 v183, 0, v183
	s_mov_b32 s2, 0xbf317218
	v_pk_fma_f32 v[180:181], v[180:181], s[2:3], v[182:183] op_sel_hi:[1,0,1]
	v_pk_fma_f32 v[178:179], v[178:179], s[2:3], v[114:115] op_sel_hi:[1,0,1]
	v_lshl_add_u64 v[114:115], v[156:157], 4, s[4:5]
	global_store_dwordx4 v[114:115], v[178:181], off

;     __device__ __forceinline__ void operator()(AccT& acc, const Unit& u, int wr, int wc, int fr, int fq, LAS unsigned char*) const {
;     ...
;                     } else if (wc == 1 && fq == 0) {
;                         const f32x4 fb = *(const f32x4*)fbias; f32x4 z = v[1][0] + fb, o;
; #pragma unroll
;                         for (int i = 0; i < 4; ++i) o[i] = fminf(z[i], 0.f) - 0.6931471805599453f * __builtin_amdgcn_logf(1.f + __builtin_amdgcn_exp2f(-fabsf(z[i]) * LOG2E));
;                         *(f32x4*)(logf + row * 4) = o;
;                     }
.LBB0_700:
	s_or_b64 exec, exec, s[8:9]
	s_andn2_b64 vcc, exec, s[70:71]
	s_cbranch_vccnz .LBB0_704
	s_and_saveexec_b64 s[8:9], s[72:73]
	s_cbranch_execz .LBB0_703
	v_mov_b64_e32 v[120:121], v[200:201]
	v_mov_b64_e32 v[122:123], v[202:203]
	s_mov_b32 s2, 0xbfb8aa3b
	v_add_f32_e32 v115, v102, v120
	v_add_f32_e32 v124, v103, v121
	v_add_f32_e32 v126, v104, v122
	v_add_f32_e32 v127, v105, v123
	v_min_f32_e32 v120, 0, v115
	v_mul_f32_e64 v115, |v115|, s2
	v_min_f32_e32 v121, 0, v124
	v_mul_f32_e64 v122, |v124|, s2
	v_mul_f32_e64 v123, |v126|, s2
	v_mul_f32_e64 v124, |v127|, s2
	v_exp_f32_e32 v115, v115
	v_exp_f32_e32 v122, v122
	v_exp_f32_e32 v123, v123
	v_exp_f32_e32 v124, v124
	v_add_f32_e32 v115, 1.0, v115
	v_add_f32_e32 v125, 1.0, v122
	v_add_f32_e32 v122, 1.0, v123
	v_add_f32_e32 v123, 1.0, v124
	v_log_f32_e32 v124, v115
	v_log_f32_e32 v122, v122
	v_log_f32_e32 v123, v123
	v_log_f32_e32 v125, v125
	v_min_f32_e32 v126, 0, v126
	v_min_f32_e32 v127, 0, v127
	s_mov_b32 s2, 0xbf317218
	v_pk_fma_f32 v[122:123], v[122:123], s[2:3], v[126:127] op_sel_hi:[1,0,1]
	v_pk_fma_f32 v[120:121], v[124:125], s[2:3], v[120:121] op_sel_hi:[1,0,1]
	v_lshl_add_u64 v[124:125], v[116:117], 4, s[4:5]
	global_store_dwordx4 v[124:125], v[120:123], off

;     __device__ __forceinline__ void operator()(AccT& acc, const Unit& u, int wr, int wc, int fr, int fq, LAS unsigned char*) const {
;     ...
;                     } else if (wc == 1 && fq == 0) {
;                         const f32x4 fb = *(const f32x4*)fbias; f32x4 z = v[1][0] + fb, o;
; #pragma unroll
;                         for (int i = 0; i < 4; ++i) o[i] = fminf(z[i], 0.f) - 0.6931471805599453f * __builtin_amdgcn_logf(1.f + __builtin_amdgcn_exp2f(-fabsf(z[i]) * LOG2E));
;                         *(f32x4*)(logf + row * 4) = o;
;                     }
.LBB0_743:
	s_or_b64 exec, exec, s[0:1]
	s_andn2_b64 vcc, exec, s[70:71]
	s_cbranch_vccnz .LBB0_747
	s_and_saveexec_b64 s[0:1], s[72:73]
	s_cbranch_execz .LBB0_746
	v_mov_b64_e32 v[104:105], v[200:201]
	v_mov_b64_e32 v[106:107], v[202:203]
	s_mov_b32 s2, 0xbfb8aa3b
	v_add_f32_e32 v99, v86, v104
	v_add_f32_e32 v108, v87, v105
	v_add_f32_e32 v110, v88, v106
	v_add_f32_e32 v111, v89, v107
	v_min_f32_e32 v104, 0, v99
	v_mul_f32_e64 v99, |v99|, s2
	v_min_f32_e32 v105, 0, v108
	v_mul_f32_e64 v106, |v108|, s2
	v_mul_f32_e64 v107, |v110|, s2
	v_mul_f32_e64 v108, |v111|, s2
	v_exp_f32_e32 v99, v99
	v_exp_f32_e32 v106, v106
	v_exp_f32_e32 v107, v107
	v_exp_f32_e32 v108, v108
	v_add_f32_e32 v99, 1.0, v99
	v_add_f32_e32 v109, 1.0, v106
	v_add_f32_e32 v106, 1.0, v107
	v_add_f32_e32 v107, 1.0, v108
	v_log_f32_e32 v108, v99
	v_log_f32_e32 v106, v106
	v_log_f32_e32 v107, v107
	v_log_f32_e32 v109, v109
	v_min_f32_e32 v110, 0, v110
	v_min_f32_e32 v111, 0, v111
	s_mov_b32 s2, 0xbf317218
	v_pk_fma_f32 v[106:107], v[106:107], s[2:3], v[110:111] op_sel_hi:[1,0,1]
	v_pk_fma_f32 v[104:105], v[108:109], s[2:3], v[104:105] op_sel_hi:[1,0,1]
	v_lshl_add_u64 v[108:109], v[100:101], 4, s[4:5]
	global_store_dwordx4 v[108:109], v[104:107], off

;     __device__ __forceinline__ void operator()(AccT& acc, const Unit& u, int wr, int wc, int fr, int fq, LAS unsigned char*) const {
;     ...
;                     } else if (wc == 1 && fq == 0) {
;                         const f32x4 fb = *(const f32x4*)fbias; f32x4 z = v[1][0] + fb, o;
; #pragma unroll
;                         for (int i = 0; i < 4; ++i) o[i] = fminf(z[i], 0.f) - 0.6931471805599453f * __builtin_amdgcn_logf(1.f + __builtin_amdgcn_exp2f(-fabsf(z[i]) * LOG2E));
;                         *(f32x4*)(logf + row * 4) = o;
;                     }
.LBB0_786:
	s_or_b64 exec, exec, s[8:9]
	s_andn2_b64 vcc, exec, s[70:71]
	s_cbranch_vccnz .LBB0_790
	s_and_saveexec_b64 s[8:9], s[72:73]
	s_cbranch_execz .LBB0_789
	v_mov_b64_e32 v[86:87], v[200:201]
	v_mov_b64_e32 v[88:89], v[202:203]
	s_mov_b32 s2, 0xbfb8aa3b
	v_add_f32_e32 v90, v70, v86
	v_add_f32_e32 v91, v71, v87
	v_add_f32_e32 v92, v72, v88
	v_add_f32_e32 v93, v73, v89
	v_min_f32_e32 v86, 0, v90
	v_mul_f32_e64 v88, |v90|, s2
	v_min_f32_e32 v87, 0, v91
	v_mul_f32_e64 v89, |v91|, s2
	v_mul_f32_e64 v90, |v92|, s2
	v_mul_f32_e64 v91, |v93|, s2
	v_exp_f32_e32 v88, v88
	v_exp_f32_e32 v89, v89
	v_exp_f32_e32 v90, v90
	v_exp_f32_e32 v91, v91
	v_add_f32_e32 v88, 1.0, v88
	v_add_f32_e32 v94, 1.0, v89
	v_add_f32_e32 v89, 1.0, v90
	v_add_f32_e32 v91, 1.0, v91
	v_log_f32_e32 v90, v88
	v_log_f32_e32 v88, v89
	v_log_f32_e32 v89, v91
	v_log_f32_e32 v91, v94
	v_min_f32_e32 v92, 0, v92
	v_min_f32_e32 v93, 0, v93
	s_mov_b32 s2, 0xbf317218
	v_pk_fma_f32 v[88:89], v[88:89], s[2:3], v[92:93] op_sel_hi:[1,0,1]
	v_pk_fma_f32 v[86:87], v[90:91], s[2:3], v[86:87] op_sel_hi:[1,0,1]
	v_lshl_add_u64 v[90:91], v[82:83], 4, s[4:5]
	global_store_dwordx4 v[90:91], v[86:89], off

;     __device__ __forceinline__ void operator()(AccT& acc, const Unit& u, int wr, int wc, int fr, int fq, LAS unsigned char*) const {
;     ...
;                     } else if (wc == 1 && fq == 0) {
;                         const f32x4 fb = *(const f32x4*)fbias; f32x4 z = v[1][0] + fb, o;
; #pragma unroll
;                         for (int i = 0; i < 4; ++i) o[i] = fminf(z[i], 0.f) - 0.6931471805599453f * __builtin_amdgcn_logf(1.f + __builtin_amdgcn_exp2f(-fabsf(z[i]) * LOG2E));
;                         *(f32x4*)(logf + row * 4) = o;
;                     }
.LBB0_829:
	s_or_b64 exec, exec, s[0:1]
	s_andn2_b64 vcc, exec, s[70:71]
	s_cbranch_vccnz .LBB0_833
	s_and_saveexec_b64 s[0:1], s[72:73]
	s_cbranch_execz .LBB0_832
	v_mov_b64_e32 v[72:73], v[200:201]
	v_mov_b64_e32 v[74:75], v[202:203]
	s_mov_b32 s2, 0xbfb8aa3b
	v_add_f32_e32 v67, v54, v72
	v_add_f32_e32 v76, v55, v73
	v_add_f32_e32 v78, v56, v74
	v_add_f32_e32 v79, v57, v75
	v_min_f32_e32 v72, 0, v67
	v_mul_f32_e64 v67, |v67|, s2
	v_min_f32_e32 v73, 0, v76
	v_mul_f32_e64 v74, |v76|, s2
	v_mul_f32_e64 v75, |v78|, s2
	v_mul_f32_e64 v76, |v79|, s2
	v_exp_f32_e32 v67, v67
	v_exp_f32_e32 v74, v74
	v_exp_f32_e32 v75, v75
	v_exp_f32_e32 v76, v76
	v_add_f32_e32 v67, 1.0, v67
	v_add_f32_e32 v77, 1.0, v74
	v_add_f32_e32 v74, 1.0, v75
	v_add_f32_e32 v75, 1.0, v76
	v_log_f32_e32 v76, v67
	v_log_f32_e32 v74, v74
	v_log_f32_e32 v75, v75
	v_log_f32_e32 v77, v77
	v_min_f32_e32 v78, 0, v78
	v_min_f32_e32 v79, 0, v79
	s_mov_b32 s2, 0xbf317218
	v_pk_fma_f32 v[74:75], v[74:75], s[2:3], v[78:79] op_sel_hi:[1,0,1]
	v_pk_fma_f32 v[72:73], v[76:77], s[2:3], v[72:73] op_sel_hi:[1,0,1]
	v_lshl_add_u64 v[76:77], v[68:69], 4, s[4:5]
	global_store_dwordx4 v[76:77], v[72:75], off

;     __device__ __forceinline__ void operator()(AccT& acc, const Unit& u, int wr, int wc, int fr, int fq, LAS unsigned char*) const {
;     ...
;                     } else if (wc == 1 && fq == 0) {
;                         const f32x4 fb = *(const f32x4*)fbias; f32x4 z = v[1][0] + fb, o;
; #pragma unroll
;                         for (int i = 0; i < 4; ++i) o[i] = fminf(z[i], 0.f) - 0.6931471805599453f * __builtin_amdgcn_logf(1.f + __builtin_amdgcn_exp2f(-fabsf(z[i]) * LOG2E));
;                         *(f32x4*)(logf + row * 4) = o;
;                     }
.LBB0_872:
	s_or_b64 exec, exec, s[8:9]
	s_andn2_b64 vcc, exec, s[70:71]
	s_cbranch_vccnz .LBB0_876
	s_and_saveexec_b64 s[8:9], s[72:73]
	s_cbranch_execz .LBB0_875
	v_mov_b64_e32 v[54:55], v[200:201]
	v_mov_b64_e32 v[56:57], v[202:203]
	s_mov_b32 s2, 0xbfb8aa3b
	v_add_f32_e32 v58, v38, v54
	v_add_f32_e32 v59, v39, v55
	v_add_f32_e32 v60, v40, v56
	v_add_f32_e32 v61, v41, v57
	v_min_f32_e32 v54, 0, v58
	v_mul_f32_e64 v56, |v58|, s2
	v_min_f32_e32 v55, 0, v59
	v_mul_f32_e64 v57, |v59|, s2
	v_mul_f32_e64 v58, |v60|, s2
	v_mul_f32_e64 v59, |v61|, s2
	v_exp_f32_e32 v56, v56
	v_exp_f32_e32 v57, v57
	v_exp_f32_e32 v58, v58
	v_exp_f32_e32 v59, v59
	v_add_f32_e32 v56, 1.0, v56
	v_add_f32_e32 v62, 1.0, v57
	v_add_f32_e32 v57, 1.0, v58
	v_add_f32_e32 v59, 1.0, v59
	v_log_f32_e32 v58, v56
	v_log_f32_e32 v56, v57
	v_log_f32_e32 v57, v59
	v_log_f32_e32 v59, v62
	v_min_f32_e32 v60, 0, v60
	v_min_f32_e32 v61, 0, v61
	s_mov_b32 s2, 0xbf317218
	v_pk_fma_f32 v[56:57], v[56:57], s[2:3], v[60:61] op_sel_hi:[1,0,1]
	v_pk_fma_f32 v[54:55], v[58:59], s[2:3], v[54:55] op_sel_hi:[1,0,1]
	v_lshl_add_u64 v[58:59], v[50:51], 4, s[4:5]
	global_store_dwordx4 v[58:59], v[54:57], off

;     __device__ __forceinline__ void operator()(AccT& acc, const Unit& u, int wr, int wc, int fr, int fq, LAS unsigned char*) const {
;     ...
;                     } else if (wc == 1 && fq == 0) {
;                         const f32x4 fb = *(const f32x4*)fbias; f32x4 z = v[1][0] + fb, o;
; #pragma unroll
;                         for (int i = 0; i < 4; ++i) o[i] = fminf(z[i], 0.f) - 0.6931471805599453f * __builtin_amdgcn_logf(1.f + __builtin_amdgcn_exp2f(-fabsf(z[i]) * LOG2E));
;                         *(f32x4*)(logf + row * 4) = o;
;                     }
.LBB0_915:
	s_or_b64 exec, exec, s[0:1]
	s_andn2_b64 vcc, exec, s[70:71]
	s_cbranch_vccnz .LBB0_919
	s_and_saveexec_b64 s[0:1], s[72:73]
	s_cbranch_execz .LBB0_918
	v_mov_b64_e32 v[40:41], v[200:201]
	v_mov_b64_e32 v[42:43], v[202:203]
	s_mov_b32 s2, 0xbfb8aa3b
	v_add_f32_e32 v35, v22, v40
	v_add_f32_e32 v44, v23, v41
	v_add_f32_e32 v46, v24, v42
	v_add_f32_e32 v47, v25, v43
	v_min_f32_e32 v40, 0, v35
	v_mul_f32_e64 v35, |v35|, s2
	v_min_f32_e32 v41, 0, v44
	v_mul_f32_e64 v42, |v44|, s2
	v_mul_f32_e64 v43, |v46|, s2
	v_mul_f32_e64 v44, |v47|, s2
	v_exp_f32_e32 v35, v35
	v_exp_f32_e32 v42, v42
	v_exp_f32_e32 v43, v43
	v_exp_f32_e32 v44, v44
	v_add_f32_e32 v35, 1.0, v35
	v_add_f32_e32 v45, 1.0, v42
	v_add_f32_e32 v42, 1.0, v43
	v_add_f32_e32 v43, 1.0, v44
	v_log_f32_e32 v44, v35
	v_log_f32_e32 v42, v42
	v_log_f32_e32 v43, v43
	v_log_f32_e32 v45, v45
	v_min_f32_e32 v46, 0, v46
	v_min_f32_e32 v47, 0, v47
	s_mov_b32 s2, 0xbf317218
	v_pk_fma_f32 v[42:43], v[42:43], s[2:3], v[46:47] op_sel_hi:[1,0,1]
	v_pk_fma_f32 v[40:41], v[44:45], s[2:3], v[40:41] op_sel_hi:[1,0,1]
	v_lshl_add_u64 v[44:45], v[36:37], 4, s[4:5]
	global_store_dwordx4 v[44:45], v[40:43], off

;     __device__ __forceinline__ void operator()(AccT& acc, const Unit& u, int wr, int wc, int fr, int fq, LAS unsigned char*) const {
;     ...
;                     } else if (wc == 1 && fq == 0) {
;                         const f32x4 fb = *(const f32x4*)fbias; f32x4 z = v[1][0] + fb, o;
; #pragma unroll
;                         for (int i = 0; i < 4; ++i) o[i] = fminf(z[i], 0.f) - 0.6931471805599453f * __builtin_amdgcn_logf(1.f + __builtin_amdgcn_exp2f(-fabsf(z[i]) * LOG2E));
;                         *(f32x4*)(logf + row * 4) = o;
;                     }
.LBB0_958:
	s_or_b64 exec, exec, s[8:9]
	s_andn2_b64 vcc, exec, s[70:71]
	s_cbranch_vccnz .LBB0_962
	s_and_saveexec_b64 s[8:9], s[72:73]
	s_cbranch_execz .LBB0_961
	v_mov_b64_e32 v[22:23], v[200:201]
	v_mov_b64_e32 v[24:25], v[202:203]
	s_mov_b32 s2, 0xbfb8aa3b
	v_add_f32_e32 v26, v6, v22
	v_add_f32_e32 v27, v7, v23
	v_add_f32_e32 v28, v8, v24
	v_add_f32_e32 v29, v9, v25
	v_min_f32_e32 v22, 0, v26
	v_mul_f32_e64 v24, |v26|, s2
	v_min_f32_e32 v23, 0, v27
	v_mul_f32_e64 v25, |v27|, s2
	v_mul_f32_e64 v26, |v28|, s2
	v_mul_f32_e64 v27, |v29|, s2
	v_exp_f32_e32 v24, v24
	v_exp_f32_e32 v25, v25
	v_exp_f32_e32 v26, v26
	v_exp_f32_e32 v27, v27
	v_add_f32_e32 v24, 1.0, v24
	v_add_f32_e32 v30, 1.0, v25
	v_add_f32_e32 v25, 1.0, v26
	v_add_f32_e32 v27, 1.0, v27
	v_log_f32_e32 v26, v24
	v_log_f32_e32 v24, v25
	v_log_f32_e32 v25, v27
	v_log_f32_e32 v27, v30
	v_min_f32_e32 v28, 0, v28
	v_min_f32_e32 v29, 0, v29
	s_mov_b32 s2, 0xbf317218
	v_pk_fma_f32 v[24:25], v[24:25], s[2:3], v[28:29] op_sel_hi:[1,0,1]
	v_pk_fma_f32 v[22:23], v[26:27], s[2:3], v[22:23] op_sel_hi:[1,0,1]
	v_lshl_add_u64 v[26:27], v[18:19], 4, s[4:5]
	global_store_dwordx4 v[26:27], v[22:25], off
